# v19: v17 + one static s_setprio 1 for waves 4-7 across the attention phase (strategy: static priority raise for the younger half)
# speedup vs baseline: 1.0081x; 1.0043x over previous
; #define LAS __attribute__((address_space(3)))
; template <int MODE>
; __device__ __forceinline__ void attn_flash(LAS unsigned char* lds, const AttnPtrs& a, int b, int hkv, int qt) {
;     ...
;     for (int i = 0; i < 2; ++i) {
;         const int hl = (MODE == 3) ? hkv * 4 + (fr & 3) : hbase + (G == 1 ? 0 : i), q = (MODE == 3) ? qw0 + 4 * i + (fr >> 2) : qw0 + (G == 1 ? 16 * i : 0) + fr;
;         float lt = lacc[i][0];
;         if (MODE == 0) { const float* sp_ = a.sinks; asm volatile("" : "+s"(sp_)); lt += fast_exp2(sp_[hl] * LOG2E - sh_loc); }
;         const float inv = lt > 0.f ? 1.0f / lt : 0.f;
;         const size_t tok = (size_t)b * SEQ + q;
;         float g0 = 0.f, g1 = 0.f, g2 = 0.f;
;         if (MODE == 3) { const float* gp = a.gates + tok * 24 + 3 * hl; const float lwv = lw[i][0]; g0 = gp[0]; g1 = gp[1] * inv; g2 = lwv > 0.f ? gp[2] / lwv : 0.f; }
; #pragma unroll
;         for (int db = 0; db < 4; ++db) {
;             f32x4 v;
;             const int col = 64 * hl + 16 * db + 4 * fq;
;             if (MODE == 3) {
;                 const u32x2 c2_ = *(const u32x2*)(a.ocmp + tok * 512 + col);
;                 v[0] = g0 * bf2f(c2_.x & 0xffffu) + g1 * o[i][db][0] + g2 * ow[i][db][0];
;                 v[1] = g0 * bf2f(c2_.x >> 16) + g1 * o[i][db][1] + g2 * ow[i][db][1];
;                 v[2] = g0 * bf2f(c2_.y & 0xffffu) + g1 * o[i][db][2] + g2 * ow[i][db][2];
; __device__ __forceinline__ void attn_phase_main(const Params& p, LAS unsigned char* lds, int l, int G) {
;     ...
;     volatile LAS float* shl = (volatile LAS float*)(lds + 131072 + 64);
;     __syncthreads();
;     if (tl_ == 0) { shl[0] = shA; shl[1] = shB; shl[2] = shC; shl[3] = shS; shl[4] = shW; }
;     __syncthreads();
;     constexpr int NU = 512 + 512 + 1024;
;     for (int ui = blockIdx.x; ui < NU; ui += G) {
;         if (ui < 512) {
;             int qt, bh;
;             if (G == 256) { const int xcd = blockIdx.x & 7, loc = blockIdx.x >> 3, hs = loc >> 4, q = loc & 15; if (ui < 256) { bh = xcd + 8 * hs; qt = 15 - q; } else { bh = xcd + 8 * (2 + hs); qt = q; } }
;             else { const int j = ui < 256 ? ui : 767 - ui; qt = 15 - (j >> 5); bh = j & 31; }
;             AttnPtrs a{(const bf16_t*)(r1 + R1_QB), (const bf16_t*)(r1 + R1_KB), (const bf16_t*)(r1 + R1_VB), O, DM, 256, 0.10206207261596575f * LOG2E, shl[1], nullptr, nullptr, nullptr, nullptr, nullptr, nullptr, 0.f};
.LBB0_219:
	s_or_b64 exec, exec, s[0:1]
	v_readlane_b32 s0, v250, 27
	v_readlane_b32 s1, v250, 28
	s_andn2_b64 vcc, exec, s[0:1]
	s_waitcnt lgkmcnt(0)
	s_barrier
	s_cbranch_vccnz .LBB0_412
	v_readlane_b32 s0, v254, 23
	v_readlane_b32 s1, v254, 24
	s_lshl_b32 s0, s0, 2
	s_ashr_i32 s1, s0, 31
	v_readlane_b32 s12, v253, 36
	s_lshl_b64 s[0:1], s[0:1], 2
	v_readlane_b32 s16, v253, 40
	v_readlane_b32 s17, v253, 41
	s_add_u32 s0, s16, s0
	s_addc_u32 s1, s17, s1
	v_writelane_b32 v254, s46, 44
	v_writelane_b32 v255, s0, 0
	v_readlane_b32 s13, v253, 37
	v_writelane_b32 v254, s47, 45
	v_writelane_b32 v255, s1, 1
	v_readlane_b32 s0, v250, 0
	s_mov_b32 s96, s0
	v_readlane_b32 s14, v253, 38
	v_readlane_b32 s15, v253, 39
	v_readlane_b32 s18, v253, 42
	v_readlane_b32 s19, v253, 43
	v_readlane_b32 s20, v253, 44
	v_readlane_b32 s21, v253, 45
	v_readlane_b32 s22, v253, 46
	v_readlane_b32 s23, v253, 47
	v_readlane_b32 s24, v253, 48
	v_readlane_b32 s25, v253, 49
	v_readlane_b32 s26, v253, 50
	v_readlane_b32 s27, v253, 51
	v_readfirstlane_b32 vcc_lo, v200
	s_nop 3
	s_lshr_b32 vcc_lo, vcc_lo, 8
	s_cmp_lg_u32 vcc_lo, 0
	s_cbranch_scc0 .Lattn_prio_done
	s_setprio 1
.Lattn_prio_done:
	s_branch .LBB0_223
.LBB0_221:
	s_waitcnt vmcnt(3)
	v_div_scale_f32 v0, s[12:13], v88, v88, 1.0
	v_rcp_f32_e32 v1, v0
	s_lshr_b32 s0, s68, 2
	s_mov_b32 s1, s69
	s_lshl_b64 s[0:1], s[0:1], 12
	v_fma_f32 v2, -v0, v1, 1.0
	v_fmac_f32_e32 v1, v2, v1
	v_div_scale_f32 v2, vcc, 1.0, v88, 1.0
	v_mul_f32_e32 v3, v2, v1
	s_waitcnt vmcnt(1)
	v_fma_f32 v4, -v0, v3, v2
	v_fmac_f32_e32 v3, v4, v1
	v_fma_f32 v0, -v0, v3, v2
	s_lshl_b32 s2, s68, 6
	v_div_fmas_f32 v0, v0, v1, v3
	s_and_b32 s2, s2, 0xc0
	v_div_fixup_f32 v0, v0, v88, 1.0
	v_cmp_lt_f32_e32 vcc, 0, v88
	v_lshl_add_u64 v[2:3], s[0:1], 0, v[186:187]
	v_readlane_b32 s14, v250, 25
	v_or_b32_e32 v8, s2, v191
	v_cndmask_b32_e32 v0, 0, v0, vcc
	v_lshlrev_b64 v[2:3], 11, v[2:3]
	v_readlane_b32 s15, v250, 26
	v_pk_mul_f32 v[4:5], v[82:83], v[0:1] op_sel_hi:[1,0]
	v_pk_mul_f32 v[6:7], v[80:81], v[0:1] op_sel_hi:[1,0]
	v_lshl_add_u64 v[2:3], s[14:15], 0, v[2:3]
	v_lshlrev_b32_e32 v16, 1, v8
	v_cvt_pk_bf16_f32 v6, v6, v7
	v_cvt_pk_bf16_f32 v7, v4, v5
	v_lshl_add_u64 v[2:3], v[2:3], 0, v[16:17]
	global_store_dwordx2 v[2:3], v[6:7], off offset:512
	v_pk_mul_f32 v[4:5], v[78:79], v[0:1] op_sel_hi:[1,0]
	v_pk_mul_f32 v[6:7], v[76:77], v[0:1] op_sel_hi:[1,0]
	v_readlane_b32 s36, v254, 33
	v_cvt_pk_bf16_f32 v6, v6, v7
	v_cvt_pk_bf16_f32 v7, v4, v5
	global_store_dwordx2 v[2:3], v[6:7], off offset:544
	v_pk_mul_f32 v[4:5], v[66:67], v[0:1] op_sel_hi:[1,0]
	v_pk_mul_f32 v[6:7], v[64:65], v[0:1] op_sel_hi:[1,0]
	s_nop 0
	v_cvt_pk_bf16_f32 v6, v6, v7
	v_cvt_pk_bf16_f32 v7, v4, v5
	global_store_dwordx2 v[2:3], v[6:7], off offset:576
	v_div_scale_f32 v6, s[12:13], v84, v84, 1.0
	v_rcp_f32_e32 v7, v6
	v_pk_mul_f32 v[4:5], v[58:59], v[0:1] op_sel_hi:[1,0]
	v_pk_mul_f32 v[0:1], v[56:57], v[0:1] op_sel_hi:[1,0]
	s_nop 0
	v_cvt_pk_bf16_f32 v0, v0, v1
	v_cvt_pk_bf16_f32 v1, v4, v5
	global_store_dwordx2 v[2:3], v[0:1], off offset:608
	v_fma_f32 v0, -v6, v7, 1.0
	v_fmac_f32_e32 v7, v0, v7
	v_div_scale_f32 v0, vcc, 1.0, v84, 1.0
	v_mul_f32_e32 v1, v0, v7
	v_fma_f32 v2, -v6, v1, v0
	v_fmac_f32_e32 v1, v2, v7
	v_fma_f32 v0, -v6, v1, v0
	v_div_fmas_f32 v0, v0, v7, v1
	v_div_fixup_f32 v0, v0, v84, 1.0
	v_cmp_lt_f32_e32 vcc, 0, v84
	v_lshl_add_u64 v[2:3], s[0:1], 0, v[184:185]
	v_lshlrev_b64 v[2:3], 11, v[2:3]
	v_cndmask_b32_e32 v0, 0, v0, vcc
	v_pk_mul_f32 v[4:5], v[74:75], v[0:1] op_sel_hi:[1,0]
	v_pk_mul_f32 v[6:7], v[72:73], v[0:1] op_sel_hi:[1,0]
	v_lshl_add_u64 v[2:3], s[14:15], 0, v[2:3]
	v_cvt_pk_bf16_f32 v6, v6, v7
	v_cvt_pk_bf16_f32 v7, v4, v5
	v_lshl_add_u64 v[2:3], v[2:3], 0, v[16:17]
	global_store_dwordx2 v[2:3], v[6:7], off offset:512
	v_pk_mul_f32 v[4:5], v[70:71], v[0:1] op_sel_hi:[1,0]
	v_pk_mul_f32 v[6:7], v[68:69], v[0:1] op_sel_hi:[1,0]
	s_nop 0
	v_cvt_pk_bf16_f32 v6, v6, v7
	v_cvt_pk_bf16_f32 v7, v4, v5
	global_store_dwordx2 v[2:3], v[6:7], off offset:544
	v_pk_mul_f32 v[4:5], v[62:63], v[0:1] op_sel_hi:[1,0]
	v_pk_mul_f32 v[6:7], v[60:61], v[0:1] op_sel_hi:[1,0]
	s_nop 0
	v_cvt_pk_bf16_f32 v6, v6, v7
	v_cvt_pk_bf16_f32 v7, v4, v5
	v_pk_mul_f32 v[4:5], v[54:55], v[0:1] op_sel_hi:[1,0]
	v_pk_mul_f32 v[0:1], v[52:53], v[0:1] op_sel_hi:[1,0]
	global_store_dwordx2 v[2:3], v[6:7], off offset:576
	v_cvt_pk_bf16_f32 v0, v0, v1
	v_cvt_pk_bf16_f32 v1, v4, v5
	global_store_dwordx2 v[2:3], v[0:1], off offset:608

; __device__ __forceinline__ void attn_phase_main(const Params& p, LAS unsigned char* lds, int l, int G) {
;     ...
;     __syncthreads();
.LBB0_412:
	s_setprio 0
	s_barrier
	s_mov_b64 s[26:27], -1
	s_branch .LBB0_152
